# v99 + converter workgroups rate-limited during GEMM1 (s_sleep 32 per weight item; more margin than 40)
# baseline (speedup 1.0000x reference)
.LBB0_80:
	s_cmp_lg_u32 s101, 2
	s_cbranch_scc1 .Lp0_nothr
	s_sleep 32
